# grid barriers: the first workgroup of each XCD to arrive issues one non-blocking L2 writeback ahead of the leader's blocking one
# baseline (speedup 1.0000x reference)
.LBB0_171:
	s_or_b64 exec, exec, s[4:5]
	v_cvt_f32_u32_e32 v4, v2
	s_waitcnt vmcnt(0)
	v_readfirstlane_b32 s0, v3
	v_sub_u32_e32 v3, 0, v2
	v_rcp_iflag_f32_e32 v4, v4
	v_add_u32_e32 v5, s0, v1
	v_mul_f32_e32 v4, 0x4f7ffffe, v4
	v_cvt_u32_f32_e32 v4, v4
	v_mul_lo_u32 v1, v3, v4
	v_mul_hi_u32 v1, v4, v1
	v_add_u32_e32 v1, v4, v1
	v_mul_hi_u32 v1, v5, v1
	v_mul_lo_u32 v3, v1, v2
	v_sub_u32_e32 v3, v5, v3
	v_add_u32_e32 v4, 1, v1
	v_cmp_ge_u32_e32 vcc, v3, v2
	s_nop 1
	v_cndmask_b32_e32 v1, v1, v4, vcc
	v_sub_u32_e32 v4, v3, v2
	v_cndmask_b32_e32 v3, v3, v4, vcc
	v_add_u32_e32 v4, 1, v1
	v_cmp_ge_u32_e32 vcc, v3, v2
	v_add_u32_e32 v3, 1, v5
	s_nop 0
	v_cndmask_b32_e32 v1, v1, v4, vcc
	v_mul_lo_u32 v4, v2, v1
	v_cmp_eq_u32_e32 vcc, v5, v4
	s_nop 4
	s_cbranch_vccz .Lewb_0
	buffer_wbl2 sc1
.Lewb_0:
	v_add_u32_e32 v2, v4, v2
	v_cmp_ne_u32_e32 vcc, v3, v2
	s_and_saveexec_b64 s[0:1], vcc
	s_xor_b64 s[4:5], exec, s[0:1]
	s_cbranch_execz .LBB0_185
	buffer_inv sc1
	v_readlane_b32 s0, v253, 45
	v_readlane_b32 s1, v253, 46
	s_waitcnt lgkmcnt(0)
	s_nop 3
	global_load_dword v0, v193, s[0:1] sc1
	s_waitcnt vmcnt(0)
	v_cmp_eq_u32_e32 vcc, v0, v1
	s_and_saveexec_b64 s[10:11], vcc
	s_cbranch_execz .LBB0_184
	s_mov_b32 s0, 1
	s_mov_b64 s[12:13], 0
	s_branch .LBB0_175
